# attention<true>: window test of key tile 4 folded into loop-invariant key offsets (interior path), on top of the all-mask-free attention<false>
# baseline (speedup 1.0000x reference)
; #define LAS __attribute__((address_space(3)))
; #define ATTN_QLOAD(W) do { const bf16_t* qr_ = Qb + ((size_t)((W).b * 24 + (W).hd) * SEQ + (size_t)((W).r * (W).L + (W).i0 + 32 * wave + l31)) * 64; \
;         _Pragma("unroll") for (int ks_ = 0; ks_ < 4; ++ks_) qv[ks_] = *(const u32x4*)(qr_ + 16 * ks_ + 8 * h); } while (0)
; __device__ __forceinline__ void attn_issue(const AUnit& w, const bf16_t* Qb, const bf16_t* Kb, const bf16_t* Vb, int tid, int wave, int lane, u32x4 (&kv)[6], u32x4 (&vv)[6]) {
;     const int ch = tid & 7;
; #pragma unroll
;     for (int i = 0; i < 6; ++i) { const int row = (tid + 512 * i) >> 3; int pk = w.i0 - 64 + row; pk = pk < 0 ? 0 : (pk >= w.L ? w.L - 1 : pk);
;         const size_t off = ((size_t)(w.b * 24 + w.hd) * SEQ + (size_t)(w.r * w.L + pk)) * 64 + ch * 8; kv[i] = *(const u32x4*)(Kb + off); vv[i] = *(const u32x4*)(Vb + off); }
; }
; __device__ __forceinline__ float attn_tile_exp(f32x16& st, int j, float tlf, float bsl, float rlo, float rhi) {
;     float sum = 0.f;
; #pragma unroll
;     for (int i = 0; i < 16; ++i) { const float tmp = (float)(32 * j - 64 + (i & 3) + 8 * (i >> 2)) + tlf;
;         float arg = __builtin_fmaf(-bsl, __builtin_fabsf(tmp), st[i]);
;         arg = (tmp >= rlo && tmp <= rhi) ? arg : -1.0e30f;
;         const float pe = __builtin_amdgcn_exp2f(arg); st[i] = pe; sum += pe; }
;     return sum;
; }
; template <bool FUSED> __device__ __forceinline__ void attn_phase(const Args& a, LAS unsigned char* lds, int tid, int lane, int wave) {
;     constexpr int HD0 = FUSED ? 0 : 8, NH = FUSED ? 8 : 16, NU = 8 * NH * 32;
;     asm volatile("" : "+v"(tid), "+v"(lane));
;     bf16_t* Qb = (bf16_t*)(a.ws + WS_Q); const bf16_t* Kb = (const bf16_t*)(a.ws + WS_K); const bf16_t* Vb = (const bf16_t*)(a.ws + WS_V); float* LSE = (float*)(a.ws + WS_LSE);
;     const int h = lane >> 5, l31 = lane & 31;
;     const int q = (lane & 15) >> 2, p = lane & 3, blk = (lane >> 4) & 1;
;     int u = blockIdx.x;
;     u32x4 kv[6], vv[6], qv[4];
;     ...
;     if (u < NU) { const AUnit w0 = attn_decode(u, HD0, NH); attn_issue(w0, Qb, Kb, Vb, tid, wave, lane, kv, vv); ATTN_QLOAD(w0); }
.LBB0_399:
	v_mov_b32_e32 v0, v178
	s_cmpk_lt_i32 s2, 0x800
	s_cbranch_scc0 .LBB0_408
	s_and_b32 s93, s2, 7
	s_lshl_b32 s93, s93, 5
	s_bfe_u32 s94, s2, 0x50003
	s_or_b32 s93, s93, s94
	s_andn2_b32 s94, s2, 0xff
	s_or_b32 s93, s93, s94
	s_cmpk_eq_i32 s54, 0x100
	s_cselect_b32 s93, s93, s2
	s_ashr_i32 s1, s93, 5
	s_lshr_b32 s4, s1, 29
	s_add_i32 s4, s1, s4
	s_and_b32 s4, s4, -8
	s_sub_i32 s1, s1, s4
	s_ashr_i32 s5, s1, 2
	s_and_b32 s5, s5, -2
	s_lshr_b32 s6, 32, s5
	s_and_b32 s0, s93, 31
	s_lshr_b32 s7, 0x2000, s5
	s_sub_i32 s5, 5, s5
	s_add_i32 s6, s6, -1
	s_lshr_b32 s5, s0, s5
	s_and_b32 s0, s6, s0
	s_ashr_i32 s4, s93, 31
	s_lshl_b32 s6, s0, 8
	s_lshr_b32 s4, s4, 24
	v_lshlrev_b32_e32 v2, 3, v0
	v_ashrrev_i32_e32 v7, 3, v0
	s_sub_i32 s8, s6, 64
	s_add_i32 s4, s93, s4
	v_and_b32_e32 v144, 56, v2
	v_add_u32_e32 v2, s8, v7
	s_add_i32 s9, s7, -1
	s_ashr_i32 s4, s4, 8
	v_min_i32_e32 v3, s9, v2
	v_cmp_lt_i32_e32 vcc, -1, v2
	s_mul_i32 s0, s4, 24
	s_mul_i32 s7, s5, s7
	v_cndmask_b32_e32 v2, 0, v3, vcc
	s_add_i32 s0, s0, s1
	v_add_u32_e32 v2, s7, v2
	s_ashr_i32 s1, s0, 31
	v_ashrrev_i32_e32 v3, 31, v2
	s_lshl_b64 s[4:5], s[0:1], 19
	v_lshlrev_b64 v[2:3], 6, v[2:3]
	v_lshl_add_u64 v[2:3], v[2:3], 0, s[4:5]
	v_or_b32_e32 v2, v2, v144
	v_lshlrev_b64 v[2:3], 1, v[2:3]
	v_lshl_add_u64 v[4:5], s[58:59], 0, v[2:3]
	v_lshl_add_u64 v[2:3], s[60:61], 0, v[2:3]
	global_load_dwordx4 v[64:67], v[4:5], off
	global_load_dwordx4 v[68:71], v[2:3], off
	v_add_u32_e32 v2, 0x200, v0
	v_ashrrev_i32_e32 v8, 3, v2
	v_add_u32_e32 v2, s8, v8
	v_min_i32_e32 v3, s9, v2
	v_cmp_lt_i32_e32 vcc, -1, v2
	s_lshl_b32 s48, s85, 5
	v_and_b32_e32 v145, 31, v186
	v_cndmask_b32_e32 v2, 0, v3, vcc
	v_add_u32_e32 v2, s7, v2
	v_ashrrev_i32_e32 v3, 31, v2
	v_lshlrev_b64 v[2:3], 6, v[2:3]
	v_lshl_add_u64 v[2:3], v[2:3], 0, s[4:5]
	v_or_b32_e32 v2, v2, v144
	v_lshlrev_b64 v[2:3], 1, v[2:3]
	v_lshl_add_u64 v[4:5], s[58:59], 0, v[2:3]
	v_lshl_add_u64 v[2:3], s[60:61], 0, v[2:3]
	global_load_dwordx4 v[72:75], v[4:5], off
	global_load_dwordx4 v[76:79], v[2:3], off
	v_add_u32_e32 v2, 0x400, v0
	v_ashrrev_i32_e32 v9, 3, v2
	v_add_u32_e32 v2, s8, v9
	v_min_i32_e32 v3, s9, v2
	v_cmp_lt_i32_e32 vcc, -1, v2
	s_lshl_b64 s[0:1], s[0:1], 20
	v_ashrrev_i32_e32 v6, 5, v186
	v_cndmask_b32_e32 v2, 0, v3, vcc
	v_add_u32_e32 v2, s7, v2
	v_ashrrev_i32_e32 v3, 31, v2
	v_lshlrev_b64 v[2:3], 6, v[2:3]
	v_lshl_add_u64 v[2:3], v[2:3], 0, s[4:5]
	v_or_b32_e32 v2, v2, v144
	v_lshlrev_b64 v[2:3], 1, v[2:3]
	v_lshl_add_u64 v[4:5], s[58:59], 0, v[2:3]
	v_lshl_add_u64 v[2:3], s[60:61], 0, v[2:3]
	global_load_dwordx4 v[80:83], v[4:5], off
	global_load_dwordx4 v[84:87], v[2:3], off
	v_add_u32_e32 v2, 0x600, v0
	v_ashrrev_i32_e32 v10, 3, v2
	v_add_u32_e32 v2, s8, v10
	v_min_i32_e32 v3, s9, v2
	v_cmp_lt_i32_e32 vcc, -1, v2
	v_lshlrev_b32_e32 v148, 3, v6
	v_ashrrev_i32_e32 v149, 31, v148
	v_cndmask_b32_e32 v2, 0, v3, vcc
	v_add_u32_e32 v2, s7, v2
	v_ashrrev_i32_e32 v3, 31, v2
	v_lshlrev_b64 v[2:3], 6, v[2:3]
	v_lshl_add_u64 v[2:3], v[2:3], 0, s[4:5]
	v_or_b32_e32 v2, v2, v144
	v_lshlrev_b64 v[2:3], 1, v[2:3]
	v_lshl_add_u64 v[4:5], s[58:59], 0, v[2:3]
	v_lshl_add_u64 v[2:3], s[60:61], 0, v[2:3]
	global_load_dwordx4 v[88:91], v[4:5], off
	global_load_dwordx4 v[92:95], v[2:3], off
	v_add_u32_e32 v2, 0x800, v0
	v_ashrrev_i32_e32 v11, 3, v2
	v_add_u32_e32 v2, s8, v11
	v_min_i32_e32 v3, s9, v2
	v_cmp_lt_i32_e32 vcc, -1, v2
	v_lshrrev_b32_e32 v1, 2, v186
	v_ashrrev_i32_e32 v188, 3, v186
	v_cndmask_b32_e32 v2, 0, v3, vcc
	v_add_u32_e32 v2, s7, v2
	v_ashrrev_i32_e32 v3, 31, v2
	v_lshlrev_b64 v[2:3], 6, v[2:3]
	v_lshl_add_u64 v[2:3], v[2:3], 0, s[4:5]
	v_or_b32_e32 v2, v2, v144
	v_lshlrev_b64 v[2:3], 1, v[2:3]
	v_lshl_add_u64 v[4:5], s[58:59], 0, v[2:3]
	v_lshl_add_u64 v[2:3], s[60:61], 0, v[2:3]
	global_load_dwordx4 v[112:115], v[4:5], off
	global_load_dwordx4 v[116:119], v[2:3], off
	v_add_u32_e32 v2, 0xa00, v0
	v_ashrrev_i32_e32 v12, 3, v2
	v_add_u32_e32 v2, s8, v12
	v_min_i32_e32 v3, s9, v2
	v_cmp_lt_i32_e32 vcc, -1, v2
	v_lshlrev_b32_e32 v29, 9, v188
	v_add_u32_e32 v190, 8, v188
	v_cndmask_b32_e32 v2, 0, v3, vcc
	v_add_u32_e32 v2, s7, v2
	v_ashrrev_i32_e32 v3, 31, v2
	v_lshlrev_b64 v[2:3], 6, v[2:3]
	v_lshl_add_u64 v[2:3], v[2:3], 0, s[4:5]
	v_or_b32_e32 v2, v2, v144
	v_lshlrev_b64 v[2:3], 1, v[2:3]
	s_add_i32 s4, s6, s7
	v_lshl_add_u64 v[4:5], s[58:59], 0, v[2:3]
	v_lshl_add_u64 v[2:3], s[60:61], 0, v[2:3]
	s_add_i32 s4, s4, s48
	global_load_dwordx4 v[120:123], v[4:5], off
	global_load_dwordx4 v[124:127], v[2:3], off
	v_add_u32_e32 v2, s4, v145
	v_ashrrev_i32_e32 v3, 31, v2
	s_add_u32 s0, s40, s0
	s_addc_u32 s1, s41, s1
	v_lshlrev_b64 v[2:3], 7, v[2:3]
	v_lshl_add_u64 v[2:3], s[0:1], 0, v[2:3]
	v_lshl_add_u64 v[2:3], v[148:149], 1, v[2:3]
	global_load_dwordx4 v[96:99], v[2:3], off
	global_load_dwordx4 v[100:103], v[2:3], off offset:32
	global_load_dwordx4 v[104:107], v[2:3], off offset:64
	global_load_dwordx4 v[108:111], v[2:3], off offset:96
	v_and_b32_e32 v2, 7, v0
	v_mbcnt_hi_u32_b32 v0, -1, v187
	v_and_b32_e32 v5, 64, v0
	v_xor_b32_e32 v4, 32, v0
	v_add_u32_e32 v5, 64, v5
	v_cmp_lt_i32_e32 vcc, v4, v5
	v_lshlrev_b32_e32 v5, 3, v186
	s_add_i32 s10, s48, 32
	v_cndmask_b32_e32 v0, v0, v4, vcc
	v_lshlrev_b32_e32 v151, 2, v0
	v_lshlrev_b32_e32 v0, 2, v6
	v_sub_u32_e32 v177, v0, v145
	v_and_or_b32 v1, v1, 3, v0
	v_lshlrev_b32_e32 v0, 1, v186
	s_lshl_b32 s0, s85, 7
	v_and_b32_e32 v0, 32, v0
	v_and_b32_e32 v13, 24, v5
	v_or_b32_e32 v22, s10, v145
	v_add_u32_e32 v23, s10, v1
	s_add_i32 s10, s48, 64
	v_and_b32_e32 v158, 0x1e00, v29
	v_lshlrev_b32_e32 v29, 9, v190
	v_add_u32_e32 v192, 24, v188
	s_add_i32 s4, s0, 0
	v_add3_u32 v13, 0, v0, v13
	v_lshlrev_b32_e32 v0, 11, v188
	s_lshl_b32 s0, s85, 12
	v_or_b32_e32 v24, s10, v145
	v_add_u32_e32 v25, s10, v1
	s_add_i32 s10, s48, 0x60
	v_and_b32_e32 v160, 0x1e00, v29
	v_lshlrev_b32_e32 v29, 9, v192
	s_waitcnt vmcnt(16)
; #define LAS __attribute__((address_space(3)))
; template <bool FUSED> __device__ __forceinline__ void attn_phase(const Args& a, LAS unsigned char* lds, int tid, int lane, int wave) {
;     ...
;         int tl = 4 * h - l31; asm volatile("" : "+v"(tl));
;         const float tlf = (float)tl;
;         const int lo_i = -iq > -64 ? -iq : -64, hi_i = (L - 1 - iq) < 64 ? (L - 1 - iq) : 64;
;         const float rlo = (float)lo_i, rhi = (float)hi_i;
;         const int wq0 = i0 + 32 * wave;
;         const bool edge = (wq0 < 64) || (wq0 + 32 > L - 64);
;         float sum = 0.f;
;         f32x16 o[2]; o[0] = f32x16{}; o[1] = f32x16{};
; #pragma unroll
;         for (int j = 0; j < 5; ++j) {
;             f32x16 st;
; #pragma unroll
;             for (int i = 0; i < 16; ++i) st[i] = -mb;
;             LAS const unsigned char* kp = lds + (32 * wave + 32 * j + l31) * KP + 16 * h;
; #pragma unroll
;             for (int ks = 0; ks < 4; ++ks) { const bf16x8 kf = *(LAS const bf16x8*)(kp + 32 * ks); st = __builtin_amdgcn_mfma_f32_32x32x16_bf16(kf, qf[ks], st, 0, 0, 0); }
;             sum += attn_tile_exp(st, j, tlf, bsl, rlo, rhi);
; #pragma unroll
;             for (int s2 = 0; s2 < 2; ++s2) { u32x4 pw; pw.x = pk2(st[8 * s2 + 0], st[8 * s2 + 1]); pw.y = pk2(st[8 * s2 + 2], st[8 * s2 + 3]); pw.z = pk2(st[8 * s2 + 4], st[8 * s2 + 5]); pw.w = pk2(st[8 * s2 + 6], st[8 * s2 + 7]);
;                 const bf16x8 pf = __builtin_bit_cast(bf16x8, pw);
;                 LAS const unsigned char* vp = lds + LDS_VOFF + (32 * wave + 32 * j + 16 * s2 + 4 * h + q) * VP + 32 * blk + 8 * p;
; #pragma unroll
;                 for (int dt = 0; dt < 2; ++dt) { const s16x4 lo = trrd(vp + dt * 64), hi = trrd(vp + 8 * VP + dt * 64);
;                     const bf16x8 vf = __builtin_shufflevector(lo, hi, 0, 1, 2, 3, 4, 5, 6, 7);
;                     o[dt] = __builtin_amdgcn_mfma_f32_32x32x16_bf16(vf, pf, o[dt], 0, 0, 0); } }
;             __builtin_amdgcn_sched_barrier(0);
;         }
;         sum += __shfl_xor(sum, 32);
;         if (un < NU) { const AUnit wq = attn_decode(un, HD0, NH); ATTN_QLOAD(wq); }
;         const float inv = __builtin_amdgcn_rcpf(sum);
;         {
;             u32x4 fo1[4], fo2[4], fg[4]; float fl1[4], fl2[4];
;             if constexpr (FUSED) {
;                 const bf16_t* Gb = (const bf16_t*)(a.ws + WS_G);
; #pragma unroll
	v_lshrrev_b32_e32 v37, 1, v188
	v_lshrrev_b32_e32 v39, 1, v190
	v_lshrrev_b32_e32 v42, 1, v192
	v_lshl_add_u32 v4, v6, 4, 0
	v_and_b32_e32 v150, 0x1800, v0
	v_and_b32_e32 v0, 56, v5
	s_add_i32 s0, s0, 0
	v_or_b32_e32 v26, s10, v145
	v_add_u32_e32 v27, s10, v1
	s_add_i32 s10, s48, 0x80
	v_and_b32_e32 v162, 0x1e00, v29
	v_bitop3_b32 v29, v6, v186, 15 bitop3:0x78
	v_add_u32_e32 v30, 2, v6
	v_add_u32_e32 v31, 4, v6
	v_add_u32_e32 v32, 6, v6
	v_add_u32_e32 v33, 8, v6
	v_add_u32_e32 v34, 10, v6
	v_add_u32_e32 v35, 12, v6
	v_add_u32_e32 v6, 14, v6
	v_xor_b32_e32 v37, v37, v186
	v_xor_b32_e32 v39, v39, v186
	v_xor_b32_e32 v42, v42, v186
	v_mov_b32_e32 v147, 0
	v_or_b32_e32 v187, s48, v145
	v_lshlrev_b32_e32 v146, 1, v0
	s_add_i32 s6, s0, 0x1f800
	v_and_b32_e32 v14, 8, v186
	s_movk_i32 s8, 0x90
	s_movk_i32 s9, 0xc0
	v_add_u32_e32 v21, s48, v1
	v_or_b32_e32 v28, s10, v145
	v_add_u32_e32 v1, s10, v1
	v_add_u32_e32 v191, 16, v188
	v_bitop3_b32 v30, v30, v186, 15 bitop3:0x78
	v_bitop3_b32 v31, v31, v186, 15 bitop3:0x78
	v_bitop3_b32 v32, v32, v186, 15 bitop3:0x78
	v_bitop3_b32 v33, v33, v186, 15 bitop3:0x78
	v_bitop3_b32 v34, v34, v186, 15 bitop3:0x78
	v_bitop3_b32 v35, v35, v186, 15 bitop3:0x78
	v_bitop3_b32 v6, v6, v186, 15 bitop3:0x78
	v_lshlrev_b32_e32 v37, 4, v37
	v_lshlrev_b32_e32 v39, 4, v39
	v_lshlrev_b32_e32 v42, 4, v42
	v_lshl_add_u32 v3, v2, 4, 0
	v_subrev_u32_e32 v153, 64, v7
	v_subrev_u32_e32 v155, 64, v8
	v_subrev_u32_e32 v159, 64, v9
	v_subrev_u32_e32 v161, 64, v10
	v_subrev_u32_e32 v163, 64, v11
	v_subrev_u32_e32 v176, 64, v12
	v_lshl_add_u64 v[156:157], s[40:41], 0, v[146:147]
	v_lshl_add_u32 v5, v145, 7, s6
	s_add_i32 s7, s4, 0x27810
	v_cmp_eq_u32_e64 s[4:5], 0, v14
	v_mul_lo_u32 v14, v7, s8
	v_mul_lo_u32 v7, v7, s9
	v_mul_lo_u32 v15, v8, s8
	v_mul_lo_u32 v8, v8, s9
	v_mul_lo_u32 v16, v9, s8
	v_mul_lo_u32 v9, v9, s9
	v_mul_lo_u32 v17, v10, s8
	v_mul_lo_u32 v10, v10, s9
	v_mul_lo_u32 v18, v11, s8
	v_mul_lo_u32 v11, v11, s9
	v_mul_lo_u32 v19, v12, s8
	v_mul_lo_u32 v12, v12, s9
	v_mul_lo_u32 v20, v187, s8
	v_mul_lo_u32 v21, v21, s9
	v_mul_lo_u32 v22, v22, s8
	v_mul_lo_u32 v23, v23, s9
	v_mul_lo_u32 v24, v24, s8
	v_mul_lo_u32 v25, v25, s9
	v_mul_lo_u32 v26, v26, s8
	v_mul_lo_u32 v27, v27, s9
	v_mul_lo_u32 v28, v28, s8
	v_mul_lo_u32 v1, v1, s9
	v_lshlrev_b32_e32 v29, 3, v29
	v_lshlrev_b32_e32 v30, 3, v30
	v_lshlrev_b32_e32 v31, 3, v31
	v_lshlrev_b32_e32 v32, 3, v32
	v_lshlrev_b32_e32 v33, 3, v33
	v_lshlrev_b32_e32 v34, 3, v34
	v_lshlrev_b32_e32 v35, 3, v35
	v_lshlrev_b32_e32 v6, 3, v6
	v_lshl_add_u32 v36, v188, 7, s6
	v_and_b32_e32 v37, 0x70, v37
	v_lshl_add_u32 v38, v190, 7, s6
	v_and_b32_e32 v39, 0x70, v39
	v_lshl_add_u32 v40, v191, 7, s6
	v_lshl_add_u32 v41, v192, 7, s6
	v_and_b32_e32 v42, 0x70, v42
	v_lshlrev_b32_e32 v146, 5, v2
	s_mov_b32 s47, 0
	v_cmp_gt_u32_e64 s[0:1], 32, v186
	v_lshl_add_u32 v189, v186, 2, s7
	s_movk_i32 s49, 0x60
	v_lshl_add_u32 v193, v188, 2, s7
	v_lshl_add_u64 v[164:165], s[44:45], 0, v[146:147]
	v_lshl_add_u64 v[166:167], v[148:149], 2, s[42:43]
	v_mov_b32_e32 v186, 0x358637bd
	v_add_u32_e32 v194, v3, v14
	v_add_u32_e32 v195, v3, v7
	v_add_u32_e32 v196, v3, v15
	v_add_u32_e32 v197, v3, v8
	v_add_u32_e32 v198, v3, v16
	v_add_u32_e32 v199, v3, v9
	v_add_u32_e32 v200, v3, v17
	v_add_u32_e32 v201, v3, v10
	v_add_u32_e32 v202, v3, v18
	v_add_u32_e32 v203, v3, v11
	v_add_u32_e32 v204, v3, v19
	v_add_u32_e32 v205, v3, v12
	v_add_u32_e32 v206, v4, v20
	v_add_u32_e32 v207, v13, v21
	v_add_u32_e32 v208, v4, v22
	v_add_u32_e32 v209, v13, v23
	v_add_u32_e32 v210, v4, v24
	v_add_u32_e32 v211, v13, v25
	v_add_u32_e32 v212, v4, v26
	v_add_u32_e32 v213, v13, v27
	v_add_u32_e32 v214, v4, v28
	v_add_u32_e32 v215, v13, v1
	s_mov_b32 s56, 0x12000000
	v_add_u32_e32 v216, v5, v29
	v_add_u32_e32 v217, v5, v30
	v_add_u32_e32 v218, v5, v31
	v_add_u32_e32 v219, v5, v32
	v_add_u32_e32 v220, v5, v33
	v_add_u32_e32 v221, v5, v34
	v_add_u32_e32 v222, v5, v35
	v_add_u32_e32 v223, v5, v6
	v_add_u32_e32 v224, v36, v37
	v_lshlrev_b32_e32 v146, 1, v0
	s_mov_b32 s57, 0xa000000
	v_add_u32_e32 v225, v38, v39
	v_add_u32_e32 v226, v40, v37
	v_add_u32_e32 v227, v41, v42
	v_mov_b32_e32 v228, 0xf149f2ca
	s_mov_b32 s46, s93
	v_cvt_f32_i32_e32 v0, v177
	s_mov_b32 s6, 0x42800000
	v_mov_b32_e32 v1, 0x7149f2ca
	v_add_f32_e32 v244, 0x42800000, v0
	v_cmp_le_f32_e64 vcc, |v244|, s6
	s_nop 1
	v_cndmask_b32_e32 v244, v1, v244, vcc
	v_add_f32_e32 v245, 0x42820000, v0
	v_cmp_le_f32_e64 vcc, |v245|, s6
	s_nop 1
	v_cndmask_b32_e32 v245, v1, v245, vcc
	v_add_f32_e32 v246, 0x42840000, v0
	v_cmp_le_f32_e64 vcc, |v246|, s6
	s_nop 1
	v_cndmask_b32_e32 v246, v1, v246, vcc
	v_add_f32_e32 v247, 0x42860000, v0
	v_cmp_le_f32_e64 vcc, |v247|, s6
	s_nop 1
	v_cndmask_b32_e32 v247, v1, v247, vcc
	v_add_f32_e32 v248, 0x42900000, v0
	v_cmp_le_f32_e64 vcc, |v248|, s6
	s_nop 1
	v_cndmask_b32_e32 v248, v1, v248, vcc
	v_add_f32_e32 v249, 0x42920000, v0
	v_cmp_le_f32_e64 vcc, |v249|, s6
	s_nop 1
	v_cndmask_b32_e32 v249, v1, v249, vcc
	v_add_f32_e32 v250, 0x42940000, v0
	v_cmp_le_f32_e64 vcc, |v250|, s6
	s_nop 1
	v_cndmask_b32_e32 v250, v1, v250, vcc
	v_add_f32_e32 v251, 0x42960000, v0
	v_cmp_le_f32_e64 vcc, |v251|, s6
	s_nop 1
	v_cndmask_b32_e32 v251, v1, v251, vcc
	v_add_f32_e32 v252, 0x42a00000, v0
	v_cmp_le_f32_e64 vcc, |v252|, s6
	s_nop 1
	v_cndmask_b32_e32 v252, v1, v252, vcc
	v_add_f32_e32 v253, 0x42a20000, v0
	v_cmp_le_f32_e64 vcc, |v253|, s6
	s_nop 1
	v_cndmask_b32_e32 v253, v1, v253, vcc
	v_add_f32_e32 v254, 0x42a40000, v0
	v_cmp_le_f32_e64 vcc, |v254|, s6
	s_nop 1
	v_cndmask_b32_e32 v254, v1, v254, vcc
	v_add_f32_e32 v255, 0x42a60000, v0
	v_cmp_le_f32_e64 vcc, |v255|, s6
	s_nop 1
	v_cndmask_b32_e32 v255, v1, v255, vcc
	v_add_f32_e32 v164, 0x42b00000, v0
	v_cmp_le_f32_e64 vcc, |v164|, s6
	s_nop 1
	v_cndmask_b32_e32 v164, v1, v164, vcc
	v_add_f32_e32 v165, 0x42b20000, v0
	v_cmp_le_f32_e64 vcc, |v165|, s6
	s_nop 1
	v_cndmask_b32_e32 v165, v1, v165, vcc
	v_add_f32_e32 v166, 0x42b40000, v0
	v_cmp_le_f32_e64 vcc, |v166|, s6
	s_nop 1
	v_cndmask_b32_e32 v166, v1, v166, vcc
	v_add_f32_e32 v167, 0x42b60000, v0
	v_cmp_le_f32_e64 vcc, |v167|, s6
	s_nop 1
	v_cndmask_b32_e32 v167, v1, v167, vcc
	s_branch .LBB0_402

; #define LAS __attribute__((address_space(3)))
; __device__ __forceinline__ unsigned pk2(float lo, float hi) { f32x2_t v = {lo, hi}; bf16x2_t b = __builtin_convertvector(v, bf16x2_t); return __builtin_bit_cast(unsigned, b); }
; template <bool FUSED> __device__ __forceinline__ void attn_phase(const Args& a, LAS unsigned char* lds, int tid, int lane, int wave) {
;     ...
;         const float bsl = __builtin_amdgcn_exp2f(-(float)(slot + 1)) * (float)w.dil * LOG2E;
;         int tl = 4 * h - l31; asm volatile("" : "+v"(tl));
;         const float tlf = (float)tl;
;         const int lo_i = -iq > -64 ? -iq : -64, hi_i = (L - 1 - iq) < 64 ? (L - 1 - iq) : 64;
;         const float rlo = (float)lo_i, rhi = (float)hi_i;
;         const int wq0 = i0 + 32 * wave;
;         const bool edge = (wq0 < 64) || (wq0 + 32 > L - 64);
;         float sum = 0.f;
;         f32x16 o[2]; o[0] = f32x16{}; o[1] = f32x16{};
; #pragma unroll
;         for (int j = 0; j < 5; ++j) {
;             f32x16 st;
; #pragma unroll
;             for (int i = 0; i < 16; ++i) st[i] = -mb;
;             LAS const unsigned char* kp = lds + (32 * wave + 32 * j + l31) * KP + 16 * h;
; #pragma unroll
;             for (int ks = 0; ks < 4; ++ks) { const bf16x8 kf = *(LAS const bf16x8*)(kp + 32 * ks); st = __builtin_amdgcn_mfma_f32_32x32x16_bf16(kf, qf[ks], st, 0, 0, 0); }
;             sum += attn_tile_exp(st, j, tlf, bsl, rlo, rhi);
; #pragma unroll
;             for (int s2 = 0; s2 < 2; ++s2) { u32x4 pw; pw.x = pk2(st[8 * s2 + 0], st[8 * s2 + 1]); pw.y = pk2(st[8 * s2 + 2], st[8 * s2 + 3]); pw.z = pk2(st[8 * s2 + 4], st[8 * s2 + 5]); pw.w = pk2(st[8 * s2 + 6], st[8 * s2 + 7]);
;                 const bf16x8 pf = __builtin_bit_cast(bf16x8, pw);
;                 LAS const unsigned char* vp = lds + LDS_VOFF + (32 * wave + 32 * j + 16 * s2 + 4 * h + q) * VP + 32 * blk + 8 * p;
; #pragma unroll
;                 for (int dt = 0; dt < 2; ++dt) { const s16x4 lo = trrd(vp + dt * 64), hi = trrd(vp + 8 * VP + dt * 64);
;                     const bf16x8 vf = __builtin_shufflevector(lo, hi, 0, 1, 2, 3, 4, 5, 6, 7);
;                     o[dt] = __builtin_amdgcn_mfma_f32_32x32x16_bf16(vf, pf, o[dt], 0, 0, 0); } }
;             __builtin_amdgcn_sched_barrier(0);
;         }
.Lattn2_join:
	v_xor_b32_e32 v32, 0x80000000, v229
	v_mov_b32_e32 v33, v32
	v_mov_b32_e32 v34, v32
	v_mov_b32_e32 v35, v32
	v_mov_b32_e32 v36, v32
	v_mov_b32_e32 v37, v32
	v_mov_b32_e32 v38, v32
	v_mov_b32_e32 v39, v32
	v_mov_b32_e32 v40, v32
	v_mov_b32_e32 v41, v32
	v_mov_b32_e32 v42, v32
	v_mov_b32_e32 v43, v32
	v_mov_b32_e32 v44, v32
	v_mov_b32_e32 v45, v32
	v_mov_b32_e32 v46, v32
	v_mov_b32_e32 v47, v32
	s_and_b32 s8, s8, 31
	s_waitcnt lgkmcnt(0)
	v_mfma_f32_32x32x16_bf16 v[0:15], v[20:23], v[96:99], v[32:47]
	ds_read_b128 v[20:23], v206 offset:64
	v_cvt_f32_ubyte0_e32 v16, s6
	v_exp_f32_e64 v29, -v16
	v_mfma_f32_32x32x16_bf16 v[0:15], v[24:27], v[100:103], v[0:15]
	s_lshl_b32 s66, s8, 8
	ds_read_b128 v[16:19], v206 offset:96
	s_add_i32 s66, s66, s48
	s_lshl_b32 s9, 1, s7
	s_lshr_b32 s7, 0x2000, s7
	s_waitcnt lgkmcnt(1)
	v_mfma_f32_32x32x16_bf16 v[0:15], v[20:23], v[104:107], v[0:15]
	v_or_b32_e32 v62, s66, v145
	v_sub_u32_e32 v20, 0, v62
	v_xad_u32 v21, v62, -1, s7
	v_cvt_f32_u32_e32 v24, s9
	v_cvt_f32_i32_e32 v171, v28
	v_max_i32_e32 v20, 0xffffffc0, v20
	v_min_i32_e32 v21, 64, v21
	s_waitcnt lgkmcnt(0)
	v_mfma_f32_32x32x16_bf16 v[0:15], v[16:19], v[108:111], v[0:15]
	v_cvt_f32_i32_e32 v168, v20
	v_cvt_f32_i32_e32 v169, v21
	v_mul_f32_e32 v24, v29, v24
	v_add_f32_e32 v16, 0xc2800000, v171
	v_mul_f32_e32 v170, 0xbfb8aa3b, v24
	v_cmp_nge_f32_e32 vcc, v16, v168
	v_cmp_nle_f32_e64 s[6:7], v16, v169
	s_nop 4
	v_fma_f32 v0, v170, |v16|, v0
	s_or_b64 vcc, vcc, s[6:7]
	v_add_f32_e32 v17, 0xc27c0000, v171
	v_cndmask_b32_e32 v0, v0, v228, vcc
	v_cmp_nge_f32_e32 vcc, v17, v168
	v_cmp_nle_f32_e64 s[6:7], v17, v169
	v_fma_f32 v1, v170, |v17|, v1
	s_or_b64 vcc, vcc, s[6:7]
	v_cndmask_b32_e32 v1, v1, v228, vcc
	v_exp_f32_e32 v17, v1
	v_add_f32_e32 v1, 0xc2780000, v171
	v_cmp_nge_f32_e32 vcc, v1, v168
	v_cmp_nle_f32_e64 s[6:7], v1, v169
	v_fma_f32 v2, v170, |v1|, v2
	s_or_b64 vcc, vcc, s[6:7]
	v_cndmask_b32_e32 v1, v2, v228, vcc
	v_exp_f32_e32 v18, v1
	v_add_f32_e32 v1, 0xc2740000, v171
	v_cmp_nge_f32_e32 vcc, v1, v168
	v_cmp_nle_f32_e64 s[6:7], v1, v169
	v_fma_f32 v2, v170, |v1|, v3
	s_or_b64 vcc, vcc, s[6:7]
	v_cndmask_b32_e32 v1, v2, v228, vcc
	v_exp_f32_e32 v19, v1
	v_add_f32_e32 v1, 0xc2600000, v171
	v_cmp_nge_f32_e32 vcc, v1, v168
	v_cmp_nle_f32_e64 s[6:7], v1, v169
	v_fma_f32 v2, v170, |v1|, v4
	s_or_b64 vcc, vcc, s[6:7]
	v_cndmask_b32_e32 v1, v2, v228, vcc
	v_exp_f32_e32 v20, v1
	v_add_f32_e32 v1, 0xc25c0000, v171
	v_cmp_nge_f32_e32 vcc, v1, v168
	v_cmp_nle_f32_e64 s[6:7], v1, v169
	v_fma_f32 v2, v170, |v1|, v5
	s_or_b64 vcc, vcc, s[6:7]
	v_cndmask_b32_e32 v1, v2, v228, vcc
	v_exp_f32_e32 v21, v1
	v_add_f32_e32 v1, 0xc2580000, v171
	v_cmp_nge_f32_e32 vcc, v1, v168
	v_cmp_nle_f32_e64 s[6:7], v1, v169
	v_fma_f32 v2, v170, |v1|, v6
	s_or_b64 vcc, vcc, s[6:7]
	v_cndmask_b32_e32 v1, v2, v228, vcc
	v_exp_f32_e32 v16, v0
	v_exp_f32_e32 v22, v1
	v_add_f32_e32 v1, 0xc2540000, v171
	v_cmp_nge_f32_e32 vcc, v1, v168
	v_cmp_nle_f32_e64 s[6:7], v1, v169
	v_fma_f32 v2, v170, |v1|, v7
	s_or_b64 vcc, vcc, s[6:7]
	v_cndmask_b32_e32 v1, v2, v228, vcc
	v_add_f32_e32 v0, 0, v16
	v_exp_f32_e32 v7, v1
	v_add_f32_e32 v1, 0xc2400000, v171
	v_add_f32_e32 v0, v17, v0
	v_cmp_nge_f32_e32 vcc, v1, v168
	v_cmp_nle_f32_e64 s[6:7], v1, v169
	v_add_f32_e32 v0, v18, v0
	v_fma_f32 v2, v170, |v1|, v8
	s_or_b64 vcc, vcc, s[6:7]
	v_add_f32_e32 v0, v19, v0
	v_cndmask_b32_e32 v1, v2, v228, vcc
	v_add_f32_e32 v0, v20, v0
	v_exp_f32_e32 v52, v1
	v_add_f32_e32 v0, v21, v0
	v_add_f32_e32 v0, v22, v0
	v_add_f32_e32 v0, v7, v0
	v_add_f32_e32 v60, v52, v0
	v_add_f32_e32 v0, 0xc23c0000, v171
	v_cmp_nge_f32_e32 vcc, v0, v168
	v_cmp_nle_f32_e64 s[6:7], v0, v169
	v_fma_f32 v1, v170, |v0|, v9
	s_or_b64 vcc, vcc, s[6:7]
	v_cndmask_b32_e32 v0, v1, v228, vcc
	v_exp_f32_e32 v61, v0
	v_add_f32_e32 v0, 0xc2380000, v171
	v_cmp_nge_f32_e32 vcc, v0, v168
	v_cmp_nle_f32_e64 s[6:7], v0, v169
	v_fma_f32 v1, v170, |v0|, v10
	s_or_b64 vcc, vcc, s[6:7]
	v_cndmask_b32_e32 v0, v1, v228, vcc
	v_exp_f32_e32 v62, v0
	v_add_f32_e32 v0, 0xc2340000, v171
	v_cmp_nge_f32_e32 vcc, v0, v168
	v_cmp_nle_f32_e64 s[6:7], v0, v169
	v_fma_f32 v1, v170, |v0|, v11
	s_or_b64 vcc, vcc, s[6:7]
	v_cndmask_b32_e32 v0, v1, v228, vcc
	v_exp_f32_e32 v63, v0
	v_add_f32_e32 v0, 0xc2200000, v171
	v_cmp_nge_f32_e32 vcc, v0, v168
	v_cmp_nle_f32_e64 s[6:7], v0, v169
	v_fma_f32 v1, v170, |v0|, v12
	s_or_b64 vcc, vcc, s[6:7]
	v_cndmask_b32_e32 v0, v1, v228, vcc
	v_exp_f32_e32 v172, v0
	v_add_f32_e32 v0, 0xc21c0000, v171
	v_cmp_nge_f32_e32 vcc, v0, v168
	v_cmp_nle_f32_e64 s[6:7], v0, v169
	v_fma_f32 v1, v170, |v0|, v13
	s_or_b64 vcc, vcc, s[6:7]
	v_cndmask_b32_e32 v0, v1, v228, vcc
	v_exp_f32_e32 v173, v0
	v_add_f32_e32 v0, 0xc2180000, v171
	v_cmp_nge_f32_e32 vcc, v0, v168
	v_cmp_nle_f32_e64 s[6:7], v0, v169
	v_fma_f32 v1, v170, |v0|, v14
	s_or_b64 vcc, vcc, s[6:7]
	v_cndmask_b32_e32 v4, v1, v228, vcc
	ds_read_b64_tr_b16 v[0:1], v207 offset:55296
	ds_read_b64_tr_b16 v[2:3], v207 offset:56832
	ds_read_b64_tr_b16 v[10:11], v207 offset:56896
	ds_read_b64_tr_b16 v[8:9], v207 offset:55360
	v_add_f32_e32 v12, 0xc2140000, v171
	v_exp_f32_e32 v174, v4
	v_cvt_pk_bf16_f32 v4, v16, v17
	v_cvt_pk_bf16_f32 v5, v18, v19
	v_cvt_pk_bf16_f32 v6, v20, v21
	v_cvt_pk_bf16_f32 v7, v22, v7
	v_cmp_nge_f32_e32 vcc, v12, v168
	v_cmp_nle_f32_e64 s[6:7], v12, v169
	s_waitcnt lgkmcnt(2)
	v_mfma_f32_32x32x16_bf16 v[16:31], v[0:3], v[4:7], 0
	v_fma_f32 v0, v170, |v12|, v15
	s_or_b64 vcc, vcc, s[6:7]
	v_cndmask_b32_e32 v53, v0, v228, vcc
	ds_read_b64_tr_b16 v[48:49], v207 offset:58368
	ds_read_b64_tr_b16 v[50:51], v207 offset:59904
	v_exp_f32_e32 v175, v53
	ds_read_b64_tr_b16 v[58:59], v207 offset:59968
	ds_read_b64_tr_b16 v[56:57], v207 offset:58432
	v_cvt_pk_bf16_f32 v52, v52, v61
	s_waitcnt lgkmcnt(4)
	v_mfma_f32_32x32x16_bf16 v[0:15], v[8:11], v[4:7], 0
	v_cvt_pk_bf16_f32 v53, v62, v63
	v_cvt_pk_bf16_f32 v54, v172, v173
	v_cvt_pk_bf16_f32 v55, v174, v175
	s_waitcnt lgkmcnt(2)
	s_nop 0
	v_mfma_f32_32x32x16_bf16 v[16:31], v[48:51], v[52:55], v[16:31]
	v_add_f32_e32 v48, v61, v60
	v_add_f32_e32 v48, v62, v48
	v_add_f32_e32 v48, v63, v48
	v_add_f32_e32 v48, v172, v48
	v_add_f32_e32 v48, v173, v48
	v_add_f32_e32 v48, v174, v48
	v_add_f32_e32 v48, v175, v48
	s_waitcnt lgkmcnt(0)
	v_mfma_f32_32x32x16_bf16 v[0:15], v[56:59], v[52:55], v[0:15]
	v_add_f32_e32 v238, 0, v48
	v_cmp_neq_f32_e32 vcc, 0xc2800000, v168
	s_mov_b64 s[6:7], vcc
	v_cmp_neq_f32_e32 vcc, 0x42800000, v169
	s_or_b64 vcc, vcc, s[6:7]
	s_cbranch_vccnz .Lattn2_slow
; #define LAS __attribute__((address_space(3)))
; __device__ __forceinline__ unsigned pk2(float lo, float hi) { f32x2_t v = {lo, hi}; bf16x2_t b = __builtin_convertvector(v, bf16x2_t); return __builtin_bit_cast(unsigned, b); }
; __device__ __forceinline__ s16x4 trrd(LAS const unsigned char* p) { return __builtin_bit_cast(s16x4, __builtin_amdgcn_ds_read_tr16_b64_v4i16((LAS v4i16_t*)p)); }
; template <bool FUSED> __device__ __forceinline__ void attn_phase(const Args& a, LAS unsigned char* lds, int tid, int lane, int wave) {
;     ...
;         for (int j = 0; j < 5; ++j) {
;             f32x16 st;
; #pragma unroll
;             for (int i = 0; i < 16; ++i) st[i] = -mb;
;             LAS const unsigned char* kp = lds + (32 * wave + 32 * j + l31) * KP + 16 * h;
; #pragma unroll
;             for (int ks = 0; ks < 4; ++ks) { const bf16x8 kf = *(LAS const bf16x8*)(kp + 32 * ks); st = __builtin_amdgcn_mfma_f32_32x32x16_bf16(kf, qf[ks], st, 0, 0, 0); }
;             sum += attn_tile_exp(st, j, tlf, bsl, rlo, rhi);
; #pragma unroll
;             for (int s2 = 0; s2 < 2; ++s2) { u32x4 pw; pw.x = pk2(st[8 * s2 + 0], st[8 * s2 + 1]); pw.y = pk2(st[8 * s2 + 2], st[8 * s2 + 3]); pw.z = pk2(st[8 * s2 + 4], st[8 * s2 + 5]); pw.w = pk2(st[8 * s2 + 6], st[8 * s2 + 7]);
;                 const bf16x8 pf = __builtin_bit_cast(bf16x8, pw);
;                 LAS const unsigned char* vp = lds + LDS_VOFF + (32 * wave + 32 * j + 16 * s2 + 4 * h + q) * VP + 32 * blk + 8 * p;
; #pragma unroll
;                 for (int dt = 0; dt < 2; ++dt) { const s16x4 lo = trrd(vp + dt * 64), hi = trrd(vp + 8 * VP + dt * 64);
;                     const bf16x8 vf = __builtin_shufflevector(lo, hi, 0, 1, 2, 3, 4, 5, 6, 7);
;                     o[dt] = __builtin_amdgcn_mfma_f32_32x32x16_bf16(vf, pf, o[dt], 0, 0, 0); } }
;             __builtin_amdgcn_sched_barrier(0);
;         }
	ds_read_b128 v[172:175], v208
	ds_read_b128 v[230:233], v208 offset:32
	v_add_f32_e32 v239, 0xc2000000, v171
	v_add_f32_e32 v240, 0xc1f80000, v171
	s_waitcnt lgkmcnt(1)
	v_mfma_f32_32x32x16_bf16 v[48:63], v[172:175], v[96:99], v[32:47]
	ds_read_b128 v[172:175], v208 offset:64
	ds_read_b128 v[234:237], v208 offset:96
	v_add_f32_e32 v241, 0xc1f00000, v171
	v_add_f32_e32 v242, 0xc1e80000, v171
	s_waitcnt lgkmcnt(2)
	v_mfma_f32_32x32x16_bf16 v[48:63], v[230:233], v[100:103], v[48:63]
	v_add_f32_e32 v230, 0xc1c00000, v171
	v_add_f32_e32 v231, 0xc1b80000, v171
	s_waitcnt lgkmcnt(1)
	v_mfma_f32_32x32x16_bf16 v[48:63], v[172:175], v[104:107], v[48:63]
	s_waitcnt lgkmcnt(0)
	v_mfma_f32_32x32x16_bf16 v[48:63], v[234:237], v[108:111], v[48:63]
	s_nop 11
	v_fma_f32 v48, v170, |v239|, v48
	v_fma_f32 v49, v170, |v240|, v49
	v_fma_f32 v50, v170, |v241|, v50
	v_fma_f32 v51, v170, |v242|, v51
	v_fma_f32 v52, v170, |v230|, v52
	v_fma_f32 v53, v170, |v231|, v53
	v_exp_f32_e32 v173, v49
	v_mov_b32_e32 v49, v53
	v_exp_f32_e32 v231, v49
	v_add_f32_e32 v49, 0xc1b00000, v171
	v_exp_f32_e32 v174, v50
	v_fma_f32 v49, v170, |v49|, v54
	v_exp_f32_e32 v172, v48
	v_exp_f32_e32 v232, v49
	v_add_f32_e32 v49, 0xc1a80000, v171
	v_fma_f32 v49, v170, |v49|, v55
	v_exp_f32_e32 v175, v51
	v_exp_f32_e32 v230, v52
	v_add_f32_e32 v48, 0, v172
	v_exp_f32_e32 v55, v49
	v_add_f32_e32 v49, 0xc1800000, v171
	v_add_f32_e32 v48, v173, v48
	v_add_f32_e32 v48, v174, v48
	v_fma_f32 v49, v170, |v49|, v56
	v_add_f32_e32 v48, v175, v48
	v_add_f32_e32 v48, v230, v48
	v_exp_f32_e32 v233, v49
	v_add_f32_e32 v48, v231, v48
	v_add_f32_e32 v48, v232, v48
	v_add_f32_e32 v48, v55, v48
	v_add_f32_e32 v234, v233, v48
	v_add_f32_e32 v48, 0xc1700000, v171
	v_fma_f32 v48, v170, |v48|, v57
	v_exp_f32_e32 v235, v48
	v_add_f32_e32 v48, 0xc1600000, v171
	v_fma_f32 v48, v170, |v48|, v58
	v_exp_f32_e32 v236, v48
	v_add_f32_e32 v48, 0xc1500000, v171
	v_fma_f32 v48, v170, |v48|, v59
	v_exp_f32_e32 v237, v48
	v_add_f32_e32 v48, 0xc1000000, v171
	v_fma_f32 v48, v170, |v48|, v60
	v_exp_f32_e32 v60, v48
	v_add_f32_e32 v48, 0xc0e00000, v171
	v_fma_f32 v48, v170, |v48|, v61
	v_exp_f32_e32 v61, v48
	v_add_f32_e32 v48, 0xc0c00000, v171
	v_fma_f32 v52, v170, |v48|, v62
	ds_read_b64_tr_b16 v[48:49], v209 offset:55296
	ds_read_b64_tr_b16 v[50:51], v209 offset:56832
	ds_read_b64_tr_b16 v[58:59], v209 offset:56896
	ds_read_b64_tr_b16 v[56:57], v209 offset:55360
	v_exp_f32_e32 v62, v52
	v_add_f32_e32 v239, 0xc0a00000, v171
	v_cvt_pk_bf16_f32 v52, v172, v173
	v_cvt_pk_bf16_f32 v53, v174, v175
	v_cvt_pk_bf16_f32 v54, v230, v231
	v_cvt_pk_bf16_f32 v55, v232, v55
	s_waitcnt lgkmcnt(2)
	s_nop 0
	v_mfma_f32_32x32x16_bf16 v[16:31], v[48:51], v[52:55], v[16:31]
	v_fma_f32 v63, v170, |v239|, v63
	ds_read_b64_tr_b16 v[48:49], v209 offset:58368
	ds_read_b64_tr_b16 v[50:51], v209 offset:59904
	v_exp_f32_e32 v63, v63
	s_waitcnt lgkmcnt(2)
	v_mfma_f32_32x32x16_bf16 v[0:15], v[56:59], v[52:55], v[0:15]
	ds_read_b64_tr_b16 v[58:59], v209 offset:59968
	ds_read_b64_tr_b16 v[56:57], v209 offset:58432
	v_cvt_pk_bf16_f32 v52, v233, v235
	v_cvt_pk_bf16_f32 v53, v236, v237
	v_cvt_pk_bf16_f32 v54, v60, v61
	v_cvt_pk_bf16_f32 v55, v62, v63
	s_waitcnt lgkmcnt(2)
	s_nop 0
	v_mfma_f32_32x32x16_bf16 v[16:31], v[48:51], v[52:55], v[16:31]
	v_add_f32_e32 v48, v235, v234
	v_add_f32_e32 v48, v236, v48
	v_add_f32_e32 v48, v237, v48
	v_add_f32_e32 v48, v60, v48
	v_add_f32_e32 v48, v61, v48
	v_add_f32_e32 v48, v62, v48
	v_add_f32_e32 v48, v63, v48
	s_waitcnt lgkmcnt(0)
	v_mfma_f32_32x32x16_bf16 v[0:15], v[56:59], v[52:55], v[0:15]
	v_add_f32_e32 v238, v238, v48
	ds_read_b128 v[172:175], v210
	ds_read_b128 v[230:233], v210 offset:32
	v_add_f32_e32 v239, 1.0, v171
	s_waitcnt lgkmcnt(1)
	v_mfma_f32_32x32x16_bf16 v[48:63], v[172:175], v[96:99], v[32:47]
	ds_read_b128 v[172:175], v210 offset:64
	ds_read_b128 v[234:237], v210 offset:96
	s_waitcnt lgkmcnt(2)
	v_mfma_f32_32x32x16_bf16 v[48:63], v[230:233], v[100:103], v[48:63]
	v_add_f32_e32 v230, 2.0, v171
	v_add_f32_e32 v231, 0x40400000, v171
	v_add_f32_e32 v232, 0x41000000, v171
	s_waitcnt lgkmcnt(1)
	v_mfma_f32_32x32x16_bf16 v[48:63], v[172:175], v[104:107], v[48:63]
	v_add_f32_e32 v233, 0x41100000, v171
	s_waitcnt lgkmcnt(0)
	v_mfma_f32_32x32x16_bf16 v[48:63], v[234:237], v[108:111], v[48:63]
	s_nop 11
	v_fma_f32 v48, v170, |v171|, v48
	v_fma_f32 v49, v170, |v239|, v49
	v_fma_f32 v50, v170, |v230|, v50
	v_fma_f32 v51, v170, |v231|, v51
	v_fma_f32 v52, v170, |v232|, v52
	v_fma_f32 v53, v170, |v233|, v53
	v_exp_f32_e32 v173, v49
	v_mov_b32_e32 v49, v53
	v_exp_f32_e32 v231, v49
	v_add_f32_e32 v49, 0x41200000, v171
	v_exp_f32_e32 v174, v50
	v_fma_f32 v49, v170, |v49|, v54
	v_exp_f32_e32 v172, v48
	v_exp_f32_e32 v232, v49
	v_add_f32_e32 v49, 0x41300000, v171
	v_fma_f32 v49, v170, |v49|, v55
	v_exp_f32_e32 v175, v51
	v_exp_f32_e32 v230, v52
	v_add_f32_e32 v48, 0, v172
	v_exp_f32_e32 v55, v49
	v_add_f32_e32 v49, 0x41800000, v171
	v_add_f32_e32 v48, v173, v48
	v_add_f32_e32 v48, v174, v48
	v_fma_f32 v49, v170, |v49|, v56
	v_add_f32_e32 v48, v175, v48
	v_add_f32_e32 v48, v230, v48
	v_exp_f32_e32 v233, v49
	v_add_f32_e32 v48, v231, v48
	v_add_f32_e32 v48, v232, v48
	v_add_f32_e32 v48, v55, v48
	v_add_f32_e32 v234, v233, v48
	v_add_f32_e32 v48, 0x41880000, v171
	v_fma_f32 v48, v170, |v48|, v57
	v_exp_f32_e32 v235, v48
	v_add_f32_e32 v48, 0x41900000, v171
	v_fma_f32 v48, v170, |v48|, v58
	v_exp_f32_e32 v236, v48
	v_add_f32_e32 v48, 0x41980000, v171
	v_fma_f32 v48, v170, |v48|, v59
	v_exp_f32_e32 v237, v48
	v_add_f32_e32 v48, 0x41c00000, v171
	v_fma_f32 v48, v170, |v48|, v60
	v_exp_f32_e32 v60, v48
	v_add_f32_e32 v48, 0x41c80000, v171
	v_fma_f32 v48, v170, |v48|, v61
	v_exp_f32_e32 v61, v48
	v_add_f32_e32 v48, 0x41d00000, v171
	v_fma_f32 v52, v170, |v48|, v62
	ds_read_b64_tr_b16 v[48:49], v211 offset:55296
	ds_read_b64_tr_b16 v[50:51], v211 offset:56832
	ds_read_b64_tr_b16 v[58:59], v211 offset:56896
	ds_read_b64_tr_b16 v[56:57], v211 offset:55360
	v_exp_f32_e32 v62, v52
	v_add_f32_e32 v239, 0x41d80000, v171
	v_cvt_pk_bf16_f32 v52, v172, v173
	v_cvt_pk_bf16_f32 v53, v174, v175
	v_cvt_pk_bf16_f32 v54, v230, v231
	v_cvt_pk_bf16_f32 v55, v232, v55
	s_waitcnt lgkmcnt(2)
; #define LAS __attribute__((address_space(3)))
; __device__ __forceinline__ unsigned pk2(float lo, float hi) { f32x2_t v = {lo, hi}; bf16x2_t b = __builtin_convertvector(v, bf16x2_t); return __builtin_bit_cast(unsigned, b); }
; __device__ __forceinline__ s16x4 trrd(LAS const unsigned char* p) { return __builtin_bit_cast(s16x4, __builtin_amdgcn_ds_read_tr16_b64_v4i16((LAS v4i16_t*)p)); }
; template <bool FUSED> __device__ __forceinline__ void attn_phase(const Args& a, LAS unsigned char* lds, int tid, int lane, int wave) {
;     ...
;         for (int j = 0; j < 5; ++j) {
;             f32x16 st;
; #pragma unroll
;             for (int i = 0; i < 16; ++i) st[i] = -mb;
;             LAS const unsigned char* kp = lds + (32 * wave + 32 * j + l31) * KP + 16 * h;
; #pragma unroll
;             for (int ks = 0; ks < 4; ++ks) { const bf16x8 kf = *(LAS const bf16x8*)(kp + 32 * ks); st = __builtin_amdgcn_mfma_f32_32x32x16_bf16(kf, qf[ks], st, 0, 0, 0); }
;             sum += attn_tile_exp(st, j, tlf, bsl, rlo, rhi);
; #pragma unroll
;             for (int s2 = 0; s2 < 2; ++s2) { u32x4 pw; pw.x = pk2(st[8 * s2 + 0], st[8 * s2 + 1]); pw.y = pk2(st[8 * s2 + 2], st[8 * s2 + 3]); pw.z = pk2(st[8 * s2 + 4], st[8 * s2 + 5]); pw.w = pk2(st[8 * s2 + 6], st[8 * s2 + 7]);
;                 const bf16x8 pf = __builtin_bit_cast(bf16x8, pw);
;                 LAS const unsigned char* vp = lds + LDS_VOFF + (32 * wave + 32 * j + 16 * s2 + 4 * h + q) * VP + 32 * blk + 8 * p;
; #pragma unroll
;                 for (int dt = 0; dt < 2; ++dt) { const s16x4 lo = trrd(vp + dt * 64), hi = trrd(vp + 8 * VP + dt * 64);
;                     const bf16x8 vf = __builtin_shufflevector(lo, hi, 0, 1, 2, 3, 4, 5, 6, 7);
;                     o[dt] = __builtin_amdgcn_mfma_f32_32x32x16_bf16(vf, pf, o[dt], 0, 0, 0); } }
;             __builtin_amdgcn_sched_barrier(0);
;         }
	s_nop 0
	v_mfma_f32_32x32x16_bf16 v[16:31], v[48:51], v[52:55], v[16:31]
	v_fma_f32 v63, v170, |v239|, v63
	ds_read_b64_tr_b16 v[48:49], v211 offset:58368
	ds_read_b64_tr_b16 v[50:51], v211 offset:59904
	v_exp_f32_e32 v63, v63
	s_waitcnt lgkmcnt(2)
	v_mfma_f32_32x32x16_bf16 v[0:15], v[56:59], v[52:55], v[0:15]
	ds_read_b64_tr_b16 v[58:59], v211 offset:59968
	ds_read_b64_tr_b16 v[56:57], v211 offset:58432
	v_cvt_pk_bf16_f32 v52, v233, v235
	v_cvt_pk_bf16_f32 v53, v236, v237
	v_cvt_pk_bf16_f32 v54, v60, v61
	v_cvt_pk_bf16_f32 v55, v62, v63
	s_waitcnt lgkmcnt(2)
	s_nop 0
	v_mfma_f32_32x32x16_bf16 v[16:31], v[48:51], v[52:55], v[16:31]
	v_add_f32_e32 v48, v235, v234
	v_add_f32_e32 v48, v236, v48
	v_add_f32_e32 v48, v237, v48
	v_add_f32_e32 v48, v60, v48
	v_add_f32_e32 v48, v61, v48
	v_add_f32_e32 v48, v62, v48
	v_add_f32_e32 v48, v63, v48
	s_waitcnt lgkmcnt(0)
	v_mfma_f32_32x32x16_bf16 v[0:15], v[56:59], v[52:55], v[0:15]
	v_add_f32_e32 v238, v238, v48
	ds_read_b128 v[172:175], v212
	ds_read_b128 v[230:233], v212 offset:32
	v_add_f32_e32 v239, 0x42000000, v171
	v_add_f32_e32 v240, 0x42040000, v171
	s_waitcnt lgkmcnt(1)
	v_mfma_f32_32x32x16_bf16 v[48:63], v[172:175], v[96:99], v[32:47]
	ds_read_b128 v[172:175], v212 offset:64
	ds_read_b128 v[234:237], v212 offset:96
	v_add_f32_e32 v241, 0x42080000, v171
	v_add_f32_e32 v242, 0x420c0000, v171
	s_waitcnt lgkmcnt(2)
	v_mfma_f32_32x32x16_bf16 v[48:63], v[230:233], v[100:103], v[48:63]
	v_add_f32_e32 v230, 0x42200000, v171
	v_add_f32_e32 v231, 0x42240000, v171
	s_waitcnt lgkmcnt(1)
	v_mfma_f32_32x32x16_bf16 v[48:63], v[172:175], v[104:107], v[48:63]
	s_waitcnt lgkmcnt(0)
	v_mfma_f32_32x32x16_bf16 v[48:63], v[234:237], v[108:111], v[48:63]
	s_nop 11
	v_fma_f32 v48, v170, |v239|, v48
	v_fma_f32 v49, v170, |v240|, v49
	v_fma_f32 v50, v170, |v241|, v50
	v_fma_f32 v51, v170, |v242|, v51
	v_fma_f32 v52, v170, |v230|, v52
	v_fma_f32 v53, v170, |v231|, v53
	v_exp_f32_e32 v173, v49
	v_mov_b32_e32 v49, v53
	v_exp_f32_e32 v231, v49
	v_add_f32_e32 v49, 0x42280000, v171
	v_exp_f32_e32 v174, v50
	v_fma_f32 v49, v170, |v49|, v54
	v_exp_f32_e32 v172, v48
	v_exp_f32_e32 v232, v49
	v_add_f32_e32 v49, 0x422c0000, v171
	v_fma_f32 v49, v170, |v49|, v55
	v_exp_f32_e32 v175, v51
	v_exp_f32_e32 v230, v52
	v_add_f32_e32 v48, 0, v172
	v_exp_f32_e32 v55, v49
	v_add_f32_e32 v49, 0x42400000, v171
	v_add_f32_e32 v48, v173, v48
	v_add_f32_e32 v48, v174, v48
	v_fma_f32 v49, v170, |v49|, v56
	v_add_f32_e32 v48, v175, v48
	v_add_f32_e32 v48, v230, v48
	v_exp_f32_e32 v233, v49
	v_add_f32_e32 v48, v231, v48
	v_add_f32_e32 v48, v232, v48
	v_add_f32_e32 v48, v55, v48
	v_add_f32_e32 v234, v233, v48
	v_add_f32_e32 v48, 0x42440000, v171
	v_fma_f32 v48, v170, |v48|, v57
	v_exp_f32_e32 v235, v48
	v_add_f32_e32 v48, 0x42480000, v171
	v_fma_f32 v48, v170, |v48|, v58
	v_exp_f32_e32 v236, v48
	v_add_f32_e32 v48, 0x424c0000, v171
	v_fma_f32 v48, v170, |v48|, v59
	v_exp_f32_e32 v237, v48
	v_add_f32_e32 v48, 0x42600000, v171
	v_fma_f32 v48, v170, |v48|, v60
	v_exp_f32_e32 v60, v48
	v_add_f32_e32 v48, 0x42640000, v171
	v_fma_f32 v48, v170, |v48|, v61
	v_exp_f32_e32 v61, v48
	v_add_f32_e32 v48, 0x42680000, v171
	v_fma_f32 v52, v170, |v48|, v62
	ds_read_b64_tr_b16 v[48:49], v213 offset:55296
	ds_read_b64_tr_b16 v[50:51], v213 offset:56832
	ds_read_b64_tr_b16 v[58:59], v213 offset:56896
	ds_read_b64_tr_b16 v[56:57], v213 offset:55360
	v_exp_f32_e32 v62, v52
	v_add_f32_e32 v239, 0x426c0000, v171
	v_cvt_pk_bf16_f32 v52, v172, v173
	v_cvt_pk_bf16_f32 v53, v174, v175
	v_cvt_pk_bf16_f32 v54, v230, v231
	v_cvt_pk_bf16_f32 v55, v232, v55
	s_waitcnt lgkmcnt(2)
	s_nop 0
	v_mfma_f32_32x32x16_bf16 v[16:31], v[48:51], v[52:55], v[16:31]
	v_fma_f32 v63, v170, |v239|, v63
	ds_read_b64_tr_b16 v[48:49], v213 offset:58368
	ds_read_b64_tr_b16 v[50:51], v213 offset:59904
	v_exp_f32_e32 v63, v63
	s_waitcnt lgkmcnt(2)
; #define LAS __attribute__((address_space(3)))
; __device__ __forceinline__ unsigned pk2(float lo, float hi) { f32x2_t v = {lo, hi}; bf16x2_t b = __builtin_convertvector(v, bf16x2_t); return __builtin_bit_cast(unsigned, b); }
; __device__ __forceinline__ s16x4 trrd(LAS const unsigned char* p) { return __builtin_bit_cast(s16x4, __builtin_amdgcn_ds_read_tr16_b64_v4i16((LAS v4i16_t*)p)); }
; __device__ __forceinline__ float attn_tile_exp(f32x16& st, int j, float tlf, float bsl, float rlo, float rhi) {
;     float sum = 0.f;
; #pragma unroll
;     for (int i = 0; i < 16; ++i) { const float tmp = (float)(32 * j - 64 + (i & 3) + 8 * (i >> 2)) + tlf;
;         float arg = __builtin_fmaf(-bsl, __builtin_fabsf(tmp), st[i]);
;         arg = (tmp >= rlo && tmp <= rhi) ? arg : -1.0e30f;
;         const float pe = __builtin_amdgcn_exp2f(arg); st[i] = pe; sum += pe; }
;     return sum;
; }
; template <bool FUSED> __device__ __forceinline__ void attn_phase(const Args& a, LAS unsigned char* lds, int tid, int lane, int wave) {
;     ...
;         for (int j = 0; j < 5; ++j) {
;             f32x16 st;
; #pragma unroll
;             for (int i = 0; i < 16; ++i) st[i] = -mb;
;             LAS const unsigned char* kp = lds + (32 * wave + 32 * j + l31) * KP + 16 * h;
; #pragma unroll
;             for (int ks = 0; ks < 4; ++ks) { const bf16x8 kf = *(LAS const bf16x8*)(kp + 32 * ks); st = __builtin_amdgcn_mfma_f32_32x32x16_bf16(kf, qf[ks], st, 0, 0, 0); }
;             sum += attn_tile_exp(st, j, tlf, bsl, rlo, rhi);
; #pragma unroll
;             for (int s2 = 0; s2 < 2; ++s2) { u32x4 pw; pw.x = pk2(st[8 * s2 + 0], st[8 * s2 + 1]); pw.y = pk2(st[8 * s2 + 2], st[8 * s2 + 3]); pw.z = pk2(st[8 * s2 + 4], st[8 * s2 + 5]); pw.w = pk2(st[8 * s2 + 6], st[8 * s2 + 7]);
;                 const bf16x8 pf = __builtin_bit_cast(bf16x8, pw);
;                 LAS const unsigned char* vp = lds + LDS_VOFF + (32 * wave + 32 * j + 16 * s2 + 4 * h + q) * VP + 32 * blk + 8 * p;
; #pragma unroll
;                 for (int dt = 0; dt < 2; ++dt) { const s16x4 lo = trrd(vp + dt * 64), hi = trrd(vp + 8 * VP + dt * 64);
;                     const bf16x8 vf = __builtin_shufflevector(lo, hi, 0, 1, 2, 3, 4, 5, 6, 7);
;                     o[dt] = __builtin_amdgcn_mfma_f32_32x32x16_bf16(vf, pf, o[dt], 0, 0, 0); } }
;             __builtin_amdgcn_sched_barrier(0);
;         }
	v_mfma_f32_32x32x16_bf16 v[0:15], v[56:59], v[52:55], v[0:15]
	ds_read_b64_tr_b16 v[58:59], v213 offset:59968
	ds_read_b64_tr_b16 v[56:57], v213 offset:58432
	v_cvt_pk_bf16_f32 v52, v233, v235
	v_cvt_pk_bf16_f32 v53, v236, v237
	v_cvt_pk_bf16_f32 v54, v60, v61
	v_cvt_pk_bf16_f32 v55, v62, v63
	s_waitcnt lgkmcnt(2)
	s_nop 0
	v_mfma_f32_32x32x16_bf16 v[16:31], v[48:51], v[52:55], v[16:31]
	v_add_f32_e32 v48, v235, v234
	v_add_f32_e32 v48, v236, v48
	v_add_f32_e32 v48, v237, v48
	v_add_f32_e32 v48, v60, v48
	v_add_f32_e32 v48, v61, v48
	v_add_f32_e32 v48, v62, v48
	v_add_f32_e32 v48, v63, v48
	s_waitcnt lgkmcnt(0)
	v_mfma_f32_32x32x16_bf16 v[0:15], v[56:59], v[52:55], v[0:15]
	v_add_f32_e32 v60, v238, v48
	ds_read_b128 v[48:51], v214
	ds_read_b128 v[52:55], v214 offset:32
	s_waitcnt lgkmcnt(1)
	v_mfma_f32_32x32x16_bf16 v[32:47], v[48:51], v[96:99], v[32:47]
	ds_read_b128 v[48:51], v214 offset:64
	ds_read_b128 v[56:59], v214 offset:96
	s_waitcnt lgkmcnt(2)
	v_mfma_f32_32x32x16_bf16 v[32:47], v[52:55], v[100:103], v[32:47]
	s_waitcnt lgkmcnt(1)
	v_mfma_f32_32x32x16_bf16 v[32:47], v[48:51], v[104:107], v[32:47]
	s_waitcnt lgkmcnt(0)
	v_mfma_f32_32x32x16_bf16 v[32:47], v[56:59], v[108:111], v[32:47]
	s_nop 11
	v_fma_f32 v32, v170, |v244|, v32
	v_fma_f32 v33, v170, |v245|, v33
	v_fma_f32 v34, v170, |v246|, v34
	v_fma_f32 v35, v170, |v247|, v35
	v_fma_f32 v36, v170, |v248|, v36
	v_fma_f32 v37, v170, |v249|, v37
	v_exp_f32_e32 v49, v33
	v_mov_b32_e32 v33, v37
	v_exp_f32_e32 v53, v33
	v_exp_f32_e32 v50, v34
	v_fma_f32 v33, v170, |v250|, v38
	v_exp_f32_e32 v48, v32
	v_exp_f32_e32 v54, v33
	v_fma_f32 v33, v170, |v251|, v39
	v_exp_f32_e32 v51, v35
	v_exp_f32_e32 v52, v36
	v_add_f32_e32 v32, 0, v48
	v_exp_f32_e32 v39, v33
	v_add_f32_e32 v32, v49, v32
	v_add_f32_e32 v32, v50, v32
	v_fma_f32 v33, v170, |v252|, v40
	v_add_f32_e32 v32, v51, v32
	v_add_f32_e32 v32, v52, v32
	v_exp_f32_e32 v55, v33
	v_add_f32_e32 v32, v53, v32
	v_add_f32_e32 v32, v54, v32
	v_add_f32_e32 v32, v39, v32
	v_add_f32_e32 v56, v55, v32
	v_fma_f32 v32, v170, |v253|, v41
	v_exp_f32_e32 v57, v32
	v_fma_f32 v32, v170, |v254|, v42
	v_exp_f32_e32 v58, v32
	v_fma_f32 v32, v170, |v255|, v43
	v_exp_f32_e32 v59, v32
	v_fma_f32 v32, v170, |v164|, v44
	v_exp_f32_e32 v44, v32
	v_fma_f32 v32, v170, |v165|, v45
	v_exp_f32_e32 v45, v32
	v_fma_f32 v36, v170, |v166|, v46
	ds_read_b64_tr_b16 v[32:33], v215 offset:55296
	ds_read_b64_tr_b16 v[34:35], v215 offset:56832
	ds_read_b64_tr_b16 v[42:43], v215 offset:56896
	ds_read_b64_tr_b16 v[40:41], v215 offset:55360
	v_exp_f32_e32 v46, v36
	v_cvt_pk_bf16_f32 v36, v48, v49
	v_cvt_pk_bf16_f32 v37, v50, v51
	v_cvt_pk_bf16_f32 v38, v52, v53
	v_cvt_pk_bf16_f32 v39, v54, v39
	s_waitcnt lgkmcnt(2)
	s_nop 0
	v_mfma_f32_32x32x16_bf16 v[16:31], v[32:35], v[36:39], v[16:31]
	v_fma_f32 v47, v170, |v167|, v47
	ds_read_b64_tr_b16 v[32:33], v215 offset:58368
	ds_read_b64_tr_b16 v[34:35], v215 offset:59904
	v_exp_f32_e32 v47, v47
	s_waitcnt lgkmcnt(2)
	v_mfma_f32_32x32x16_bf16 v[0:15], v[40:43], v[36:39], v[0:15]
	ds_read_b64_tr_b16 v[42:43], v215 offset:59968
	ds_read_b64_tr_b16 v[40:41], v215 offset:58432
	v_cvt_pk_bf16_f32 v36, v55, v57
	v_cvt_pk_bf16_f32 v37, v58, v59
	v_cvt_pk_bf16_f32 v38, v44, v45
	v_cvt_pk_bf16_f32 v39, v46, v47
	s_waitcnt lgkmcnt(2)
	s_nop 0
	v_mfma_f32_32x32x16_bf16 v[16:31], v[32:35], v[36:39], v[16:31]
	v_add_f32_e32 v32, v57, v56
	v_add_f32_e32 v32, v58, v32
	v_add_f32_e32 v32, v59, v32
	v_add_f32_e32 v32, v44, v32
	v_add_f32_e32 v32, v45, v32
	v_add_f32_e32 v32, v46, v32
	v_add_f32_e32 v32, v47, v32
	s_waitcnt lgkmcnt(0)
	v_mfma_f32_32x32x16_bf16 v[0:15], v[40:43], v[36:39], v[0:15]
	v_add_f32_e32 v236, v60, v32
	s_branch .Lattn2_end

; #define ATTN_QLOAD(W) do { const bf16_t* qr_ = Qb + ((size_t)((W).b * 24 + (W).hd) * SEQ + (size_t)((W).r * (W).L + (W).i0 + 32 * wave + l31)) * 64; \
;         _Pragma("unroll") for (int ks_ = 0; ks_ < 4; ++ks_) qv[ks_] = *(const u32x4*)(qr_ + 16 * ks_ + 8 * h); } while (0)
; template <bool FUSED> __device__ __forceinline__ void attn_phase(const Args& a, LAS unsigned char* lds, int tid, int lane, int wave) {
;     ...
;         sum += __shfl_xor(sum, 32);
;         if (un < NU) { const AUnit wq = attn_decode(un, HD0, NH); ATTN_QLOAD(wq); }
.Lattn2_end:
	ds_bpermute_b32 v237, v151, v236
	s_andn2_b64 vcc, exec, s[44:45]
	s_cbranch_vccnz .LBB0_406
	s_ashr_i32 s7, s64, 5
	s_lshr_b32 s8, s7, 29
	s_add_i32 s8, s7, s8
	s_and_b32 s8, s8, -8
	s_sub_i32 s7, s7, s8
	s_ashr_i32 s9, s7, 2
	s_ashr_i32 s8, s64, 31
	s_and_b32 s9, s9, -2
	s_lshr_b32 s8, s8, 24
	s_lshr_b32 s10, 32, s9
	s_and_b32 s6, s64, 31
	s_add_i32 s8, s64, s8
	s_lshr_b32 s11, 0x2000, s9
	s_sub_i32 s9, 5, s9
	s_add_i32 s10, s10, -1
	s_ashr_i32 s8, s8, 8
	s_lshr_b32 s9, s6, s9
	s_and_b32 s6, s10, s6
	s_lshl_b32 s10, s6, 8
	s_mul_i32 s6, s8, 24
	s_add_i32 s6, s6, s7
	s_mul_i32 s9, s9, s11
	s_ashr_i32 s7, s6, 31
	s_add_i32 s10, s10, s9
	v_add_u32_e32 v32, s10, v187
	s_lshl_b64 s[6:7], s[6:7], 20
	v_ashrrev_i32_e32 v33, 31, v32
	s_add_u32 s6, s40, s6
	s_addc_u32 s7, s41, s7
	v_lshlrev_b64 v[32:33], 7, v[32:33]
	v_lshl_add_u64 v[32:33], s[6:7], 0, v[32:33]
	v_lshl_add_u64 v[32:33], v[148:149], 1, v[32:33]
	global_load_dwordx4 v[96:99], v[32:33], off
	global_load_dwordx4 v[100:103], v[32:33], off offset:32
	global_load_dwordx4 v[104:107], v[32:33], off offset:64
	global_load_dwordx4 v[108:111], v[32:33], off offset:96
